# 256-job GEMM phases (256x192 tiles): job index permuted so each XCD covers 8x4 tile sub-grid (L2 operand sharing)
# speedup vs baseline: 1.0019x; 1.0019x over previous
.LBB0_37:
	s_andn2_b64 vcc, exec, s[0:1]
	s_cbranch_vccnz .LBB0_145
	v_readlane_b32 s0, v253, 63
	v_readlane_b32 s1, v254, 0
	s_andn2_b64 vcc, exec, s[0:1]
	s_nop 0
	v_cndmask_b32_e64 v0, 0, 1, s[0:1]
	v_cmp_ne_u32_e64 s[2:3], 1, v0
	s_mov_b64 s[0:1], -1
	s_cbranch_vccnz .LBB0_117
	s_cmpk_gt_i32 s74, 0xff
	s_cbranch_scc1 .LBB0_116
	s_and_b32 s98, s74, 7
	s_lshl_b32 s98, s98, 5
	s_lshr_b32 s99, s74, 3
	s_or_b32 s0, s98, s99
	s_branch .LBB0_42

.LBB0_189:
	s_and_b64 vcc, exec, s[0:1]
	s_cbranch_vccz .LBB0_228
	v_readlane_b32 s0, v253, 63
	v_readlane_b32 s1, v254, 0
	s_andn2_b64 vcc, exec, s[0:1]
	s_nop 0
	v_cndmask_b32_e64 v0, 0, 1, s[0:1]
	v_cmp_ne_u32_e64 s[2:3], 1, v0
	s_mov_b64 s[0:1], -1
	s_cbranch_vccnz .LBB0_200
	s_cmpk_gt_i32 s74, 0xff
	s_cbranch_scc1 .LBB0_199
	s_and_b32 s98, s74, 7
	s_lshl_b32 s98, s98, 5
	s_lshr_b32 s99, s74, 3
	s_or_b32 s0, s98, s99
	s_branch .LBB0_194
